# glapost: loop-invariant gla_norm loads hoisted out of the token loop (copied from spare VGPRs each iteration)
# speedup vs baseline: 1.0027x; 1.0027x over previous
.LBB0_489:
	s_cmp_gt_i32 s44, 5
	s_cselect_b64 s[2:3], -1, 0
	s_cmp_lt_i32 s45, 6
	s_cselect_b64 s[4:5], -1, 0
	s_or_b64 s[2:3], s[2:3], s[4:5]
	v_bfe_u32 v131, v0, 6, 4
	s_and_b64 vcc, exec, s[2:3]
	v_lshl_or_b32 v130, s66, 2, v131
	s_cbranch_vccnz .LBB0_547
	s_load_dword s33, s[0:1], 0xf0
	s_waitcnt vmcnt(1)
	v_lshl_or_b32 v26, s66, 2, v131
	s_add_u32 s2, s0, 0xf0
	s_movk_i32 s4, 0x3000
	v_and_b32_e32 v1, 0x3ff, v0
	s_addc_u32 s3, s1, 0
	v_cmp_gt_i32_e32 vcc, s4, v26
	s_and_saveexec_b64 s[46:47], vcc
	s_cbranch_execz .LBB0_493
	v_mbcnt_lo_u32_b32 v2, -1, 0
	v_mbcnt_hi_u32_b32 v2, -1, v2
	v_and_b32_e32 v4, 64, v2
	v_xor_b32_e32 v3, 1, v2
	v_add_u32_e32 v4, 64, v4
	v_cmp_lt_i32_e32 vcc, v3, v4
	v_ashrrev_i32_e32 v27, 31, v26
	s_waitcnt lgkmcnt(0)
	s_lshl_b32 s48, s33, 2
	v_cndmask_b32_e32 v3, v2, v3, vcc
	v_lshlrev_b32_e32 v42, 2, v3
	v_xor_b32_e32 v3, 2, v2
	v_cmp_lt_i32_e32 vcc, v3, v4
	s_mov_b64 s[4:5], 0x18d2401c
	s_ashr_i32 s49, s48, 31
	v_cndmask_b32_e32 v3, v2, v3, vcc
	v_lshlrev_b32_e32 v43, 2, v3
	v_xor_b32_e32 v3, 4, v2
	v_cmp_lt_i32_e32 vcc, v3, v4
	s_mov_b32 s54, 0xfe7fffe4
	s_mov_b32 s56, 0xf85fffe4
	v_cndmask_b32_e32 v3, v2, v3, vcc
	v_lshlrev_b32_e32 v44, 2, v3
	v_xor_b32_e32 v3, 8, v2
	v_cmp_lt_i32_e32 vcc, v3, v4
	v_and_b32_e32 v4, 63, v1
	s_lshl_b64 s[50:51], s[48:49], 11
	v_cndmask_b32_e32 v2, v2, v3, vcc
	v_lshlrev_b32_e32 v45, 2, v2
	v_lshlrev_b32_e32 v2, 6, v1
	v_and_b32_e32 v2, 0x3c0, v2
	v_mov_b32_e32 v3, 0
	v_lshl_add_u64 v[28:29], s[92:93], 0, v[2:3]
	v_lshlrev_b64 v[2:3], 11, v[26:27]
	v_lshl_or_b32 v2, v4, 5, v2
	v_lshl_add_u64 v[2:3], s[42:43], 0, v[2:3]
	s_waitcnt vmcnt(0)
	v_lshl_add_u64 v[30:31], v[2:3], 0, s[4:5]
	s_mov_b64 s[52:53], 0
	s_mov_b32 s55, -1
	s_mov_b32 s57, -1
	s_mov_b32 s49, 0xf8600000
	v_mov_b32_e32 v27, 0x358637bd
	s_mov_b32 s58, 0x800000
	s_movk_i32 s59, 0x2fff
	global_load_dwordx4 v[224:227], v[28:29], off offset:48
	global_load_dwordx4 v[228:231], v[28:29], off offset:32
	global_load_dwordx4 v[232:235], v[28:29], off offset:16
	global_load_dwordx4 v[236:239], v[28:29], off
	s_waitcnt vmcnt(0)
.LBB0_492:
	v_add_co_u32_e32 v32, vcc, 0xfe800000, v30
	global_load_dwordx4 v[18:21], v[30:31], off offset:-12
	global_load_dwordx4 v[22:25], v[30:31], off offset:-28
	v_addc_co_u32_e32 v33, vcc, -1, v31, vcc
	v_add_co_u32_e32 v50, vcc, s49, v30
	v_lshl_add_u64 v[36:37], v[30:31], 0, s[54:55]
	v_lshl_add_u64 v[34:35], v[30:31], 0, s[56:57]
	v_mov_b32_e32 v2, v224
	v_mov_b32_e32 v3, v225
	v_mov_b32_e32 v4, v226
	v_mov_b32_e32 v5, v227
	v_mov_b32_e32 v6, v228
	v_mov_b32_e32 v7, v229
	v_mov_b32_e32 v8, v230
	v_mov_b32_e32 v9, v231
	v_mov_b32_e32 v10, v232
	v_mov_b32_e32 v11, v233
	v_mov_b32_e32 v12, v234
	v_mov_b32_e32 v13, v235
	v_mov_b32_e32 v14, v236
	v_mov_b32_e32 v15, v237
	v_mov_b32_e32 v16, v238
	v_mov_b32_e32 v17, v239
	global_load_dwordx4 v[38:41], v[32:33], off offset:-28
	global_load_dwordx4 v[46:49], v[36:37], off offset:16
	v_addc_co_u32_e32 v51, vcc, -1, v31, vcc
	global_load_dwordx4 v[50:53], v[50:51], off offset:-28
	s_nop 0
	global_load_dwordx4 v[34:37], v[34:35], off offset:16
	v_add_u32_e32 v26, s48, v26
	v_cmp_lt_i32_e64 s[4:5], s59, v26
	s_or_b64 s[52:53], s[4:5], s[52:53]
	v_lshl_add_u64 v[30:31], v[30:31], 0, s[50:51]
	s_waitcnt vmcnt(5)
	v_lshlrev_b32_e32 v62, 16, v20
	s_waitcnt vmcnt(4)
	v_lshlrev_b32_e32 v54, 16, v22
	v_and_b32_e32 v55, 0xffff0000, v22
	v_lshlrev_b32_e32 v56, 16, v23
	v_and_b32_e32 v57, 0xffff0000, v23
	v_lshlrev_b32_e32 v58, 16, v24
	v_and_b32_e32 v59, 0xffff0000, v24
	v_lshlrev_b32_e32 v60, 16, v25
	v_and_b32_e32 v61, 0xffff0000, v25
	v_lshlrev_b32_e32 v24, 16, v18
	v_and_b32_e32 v25, 0xffff0000, v18
	v_lshlrev_b32_e32 v22, 16, v19
	v_and_b32_e32 v23, 0xffff0000, v19
	v_and_b32_e32 v63, 0xffff0000, v20
	v_lshlrev_b32_e32 v18, 16, v21
	v_and_b32_e32 v19, 0xffff0000, v21
	s_waitcnt vmcnt(3)
	v_lshlrev_b32_e32 v64, 16, v38
	v_and_b32_e32 v65, 0xffff0000, v38
	v_lshlrev_b32_e32 v38, 16, v39
	v_and_b32_e32 v39, 0xffff0000, v39
	v_lshlrev_b32_e32 v66, 16, v40
	v_and_b32_e32 v67, 0xffff0000, v40
	v_lshlrev_b32_e32 v40, 16, v41
	v_and_b32_e32 v41, 0xffff0000, v41
	s_waitcnt vmcnt(2)
	v_lshlrev_b32_e32 v68, 16, v46
	v_and_b32_e32 v69, 0xffff0000, v46
	v_lshlrev_b32_e32 v46, 16, v47
	v_and_b32_e32 v47, 0xffff0000, v47
	v_lshlrev_b32_e32 v20, 16, v48
	v_and_b32_e32 v21, 0xffff0000, v48
	v_lshlrev_b32_e32 v48, 16, v49
	v_and_b32_e32 v49, 0xffff0000, v49
	s_waitcnt vmcnt(0)
	v_lshlrev_b32_e32 v84, 16, v34
	v_and_b32_e32 v85, 0xffff0000, v34
	v_lshlrev_b32_e32 v86, 16, v35
	v_and_b32_e32 v87, 0xffff0000, v35
	v_lshlrev_b32_e32 v88, 16, v36
	v_and_b32_e32 v89, 0xffff0000, v36
	v_lshlrev_b32_e32 v90, 16, v37
	v_and_b32_e32 v91, 0xffff0000, v37
	v_pk_add_f32 v[18:19], v[48:49], v[18:19]
	v_pk_add_f32 v[20:21], v[20:21], v[62:63]
	v_pk_add_f32 v[22:23], v[46:47], v[22:23]
	v_pk_add_f32 v[24:25], v[68:69], v[24:25]
	v_pk_add_f32 v[34:35], v[40:41], v[60:61]
	v_pk_add_f32 v[36:37], v[66:67], v[58:59]
	v_pk_add_f32 v[38:39], v[38:39], v[56:57]
	v_pk_add_f32 v[40:41], v[64:65], v[54:55]
	v_lshlrev_b32_e32 v80, 16, v52
	v_and_b32_e32 v81, 0xffff0000, v52
	v_lshlrev_b32_e32 v82, 16, v53
	v_and_b32_e32 v83, 0xffff0000, v53
	v_mov_b32_e32 v48, v21
	v_mov_b32_e32 v49, v19
	v_mul_f32_e32 v62, 0xbfb8aa3b, v88
	v_mul_f32_e32 v63, 0xbfb8aa3b, v89
	v_mov_b32_e32 v52, v25
	v_mov_b32_e32 v53, v23
	v_mov_b32_e32 v56, v37
	v_mov_b32_e32 v57, v35
	v_pk_mul_f32 v[58:59], v[38:39], v[38:39]
	v_pk_mul_f32 v[60:61], v[40:41], v[40:41]
	v_lshlrev_b32_e32 v76, 16, v50
	v_and_b32_e32 v77, 0xffff0000, v50
	v_lshlrev_b32_e32 v78, 16, v51
	v_and_b32_e32 v79, 0xffff0000, v51
	v_mov_b32_e32 v46, v20
	v_mov_b32_e32 v47, v18
	v_mov_b32_e32 v50, v24
	v_mov_b32_e32 v51, v22
	v_mul_f32_e32 v66, 0xbfb8aa3b, v84
	v_mul_f32_e32 v67, 0xbfb8aa3b, v85
	v_mov_b32_e32 v54, v36
	v_mov_b32_e32 v55, v34
	v_pk_mul_f32 v[48:49], v[48:49], v[48:49]
	v_exp_f32_e32 v62, v62
	v_exp_f32_e32 v63, v63
	v_pk_mul_f32 v[52:53], v[52:53], v[52:53]
	v_pk_mul_f32 v[56:57], v[56:57], v[56:57]
	v_add_f32_e32 v94, v58, v59
	v_add_f32_e32 v60, v60, v61
	v_mul_f32_e32 v92, 0xbfb8aa3b, v90
	v_mul_f32_e32 v93, 0xbfb8aa3b, v91
	v_exp_f32_e32 v66, v66
	v_exp_f32_e32 v67, v67
	v_pk_fma_f32 v[46:47], v[46:47], v[46:47], v[48:49]
	v_pk_fma_f32 v[48:49], v[50:51], v[50:51], v[52:53]
	v_pk_fma_f32 v[50:51], v[54:55], v[54:55], v[56:57]
	v_add_f32_e32 v52, v60, v94
	v_mul_f32_e32 v64, 0xbfb8aa3b, v86
	v_mul_f32_e32 v65, 0xbfb8aa3b, v87
	v_mul_f32_e32 v68, 0xbfb8aa3b, v82
	v_mul_f32_e32 v69, 0xbfb8aa3b, v83
	v_exp_f32_e32 v58, v92
	v_exp_f32_e32 v59, v93
	v_add_f32_e32 v50, v52, v50
	v_mul_f32_e32 v70, 0xbfb8aa3b, v80
	v_mul_f32_e32 v71, 0xbfb8aa3b, v81
	v_exp_f32_e32 v64, v64
	v_exp_f32_e32 v65, v65
	v_exp_f32_e32 v68, v68
	v_exp_f32_e32 v69, v69
	v_add_f32_e32 v92, v50, v51
	v_mul_f32_e32 v72, 0xbfb8aa3b, v78
	v_mul_f32_e32 v73, 0xbfb8aa3b, v79
	v_exp_f32_e32 v70, v70
	v_exp_f32_e32 v71, v71
	v_pk_add_f32 v[50:51], v[62:63], 1.0 op_sel_hi:[1,0]
	v_add_f32_e32 v48, v92, v48
	v_mul_f32_e32 v74, 0xbfb8aa3b, v76
	v_mul_f32_e32 v75, 0xbfb8aa3b, v77
	v_exp_f32_e32 v72, v72
	v_exp_f32_e32 v73, v73
	v_pk_add_f32 v[54:55], v[66:67], 1.0 op_sel_hi:[1,0]
	v_div_scale_f32 v66, s[4:5], v51, v51, v89
	v_add_f32_e32 v48, v48, v49
	v_exp_f32_e32 v74, v74
	v_exp_f32_e32 v75, v75
	v_pk_add_f32 v[58:59], v[58:59], 1.0 op_sel_hi:[1,0]
	v_rcp_f32_e32 v113, v66
	v_add_f32_e32 v46, v48, v46
	v_pk_add_f32 v[52:53], v[64:65], 1.0 op_sel_hi:[1,0]
	v_pk_add_f32 v[56:57], v[68:69], 1.0 op_sel_hi:[1,0]
	v_div_scale_f32 v68, s[4:5], v50, v50, v88
	v_div_scale_f32 v49, s[4:5], v59, v59, v91
	v_add_f32_e32 v46, v46, v47
	v_pk_add_f32 v[60:61], v[70:71], 1.0 op_sel_hi:[1,0]
	v_div_scale_f32 v70, s[4:5], v53, v53, v87
	v_rcp_f32_e32 v114, v68
	v_rcp_f32_e32 v127, v49
	ds_bpermute_b32 v47, v42, v46
	v_pk_add_f32 v[62:63], v[72:73], 1.0 op_sel_hi:[1,0]
	v_div_scale_f32 v72, s[4:5], v52, v52, v86
	v_div_scale_f32 v111, s[4:5], v58, v58, v90
	v_rcp_f32_e32 v115, v70
	v_pk_add_f32 v[64:65], v[74:75], 1.0 op_sel_hi:[1,0]
	v_div_scale_f32 v74, s[4:5], v55, v55, v85
	v_div_scale_f32 v94, s[4:5], v57, v57, v83
	v_rcp_f32_e32 v116, v72
	v_rcp_f32_e32 v128, v111
	v_fma_f32 v48, -v66, v113, 1.0
	v_div_scale_f32 v67, vcc, v89, v51, v89
	v_div_scale_f32 v92, s[4:5], v54, v54, v84
	v_rcp_f32_e32 v117, v74
	v_rcp_f32_e32 v119, v94
	v_fmac_f32_e32 v113, v48, v113
	v_rcp_f32_e32 v118, v92
	v_fma_f32 v129, -v68, v114, 1.0
	v_fma_f32 v144, -v49, v127, 1.0
	v_mul_f32_e32 v48, v67, v113
	v_div_scale_f32 v69, s[34:35], v88, v50, v88
	v_div_scale_f32 v96, s[4:5], v56, v56, v82
	v_div_scale_f32 v110, s[8:9], v91, v59, v91
	v_fma_f32 v132, -v70, v115, 1.0
	v_fmac_f32_e32 v114, v129, v114
	v_fmac_f32_e32 v127, v144, v127
	v_fma_f32 v146, -v66, v48, v67
	s_waitcnt lgkmcnt(0)
	v_add_f32_e32 v160, v46, v47
	v_div_scale_f32 v71, s[30:31], v87, v53, v87
	v_div_scale_f32 v98, s[4:5], v61, v61, v81
	v_div_scale_f32 v100, s[4:5], v60, v60, v80
	v_div_scale_f32 v102, s[4:5], v63, v63, v79
	v_div_scale_f32 v104, s[4:5], v62, v62, v78
	v_div_scale_f32 v106, s[4:5], v65, v65, v77
	v_div_scale_f32 v108, s[4:5], v64, v64, v76
	v_rcp_f32_e32 v120, v96
	v_fma_f32 v133, -v72, v116, 1.0
	v_fma_f32 v145, -v111, v128, 1.0
	v_fmac_f32_e32 v115, v132, v115
	v_mul_f32_e32 v129, v69, v114
	v_mul_f32_e32 v144, v110, v127
	v_fmac_f32_e32 v48, v146, v113
	ds_bpermute_b32 v146, v43, v160
	v_div_scale_f32 v73, s[28:29], v86, v52, v86
	v_div_scale_f32 v112, s[4:5], v90, v58, v90
	v_rcp_f32_e32 v121, v98
	v_fma_f32 v134, -v74, v117, 1.0
	v_fma_f32 v136, -v94, v119, 1.0
	v_fmac_f32_e32 v116, v133, v116
	v_fmac_f32_e32 v128, v145, v128
	v_mul_f32_e32 v132, v71, v115
	v_fma_f32 v147, -v68, v129, v69
	v_fma_f32 v46, -v49, v144, v110
	v_div_scale_f32 v75, s[26:27], v85, v55, v85
	v_div_scale_f32 v95, s[22:23], v83, v57, v83
	v_rcp_f32_e32 v122, v100
	v_fma_f32 v135, -v92, v118, 1.0
	v_fmac_f32_e32 v117, v134, v117
	v_fmac_f32_e32 v119, v136, v119
	v_mul_f32_e32 v133, v73, v116
	v_mul_f32_e32 v145, v112, v128
	v_fma_f32 v148, -v70, v132, v71
	v_fmac_f32_e32 v129, v147, v114
	v_fmac_f32_e32 v144, v46, v127
	v_fma_f32 v46, -v66, v48, v67
	v_div_scale_f32 v93, s[24:25], v84, v54, v84
	v_rcp_f32_e32 v123, v102
	v_fmac_f32_e32 v118, v135, v118
	v_mul_f32_e32 v134, v75, v117
	v_mul_f32_e32 v136, v95, v119
	v_fma_f32 v149, -v72, v133, v73
	v_fma_f32 v47, -v111, v145, v112
	v_fmac_f32_e32 v132, v148, v115
	v_fma_f32 v66, -v68, v129, v69
	v_div_fmas_f32 v46, v46, v113, v48
	s_mov_b64 vcc, s[34:35]
	v_rcp_f32_e32 v124, v104
	v_fma_f32 v137, -v96, v120, 1.0
	v_mul_f32_e32 v135, v93, v118
	v_fma_f32 v150, -v74, v134, v75
	v_fma_f32 v152, -v94, v136, v95
	v_fmac_f32_e32 v133, v149, v116
	v_fmac_f32_e32 v145, v47, v128
	v_fma_f32 v67, -v70, v132, v71
	v_div_fixup_f32 v47, v46, v51, v89
	v_div_fmas_f32 v46, v66, v114, v129
	s_mov_b64 vcc, s[30:31]
	v_div_scale_f32 v97, s[20:21], v82, v56, v82
	v_rcp_f32_e32 v125, v106
	v_fma_f32 v138, -v98, v121, 1.0
	v_fmac_f32_e32 v120, v137, v120
	v_fma_f32 v151, -v92, v135, v93
	v_fmac_f32_e32 v134, v150, v117
	v_fmac_f32_e32 v136, v152, v119
	v_fma_f32 v68, -v72, v133, v73
	v_div_fmas_f32 v48, v67, v115, v132
	s_mov_b64 vcc, s[28:29]
	s_waitcnt lgkmcnt(0)
	v_add_f32_e32 v66, v160, v146
	v_div_scale_f32 v99, s[18:19], v81, v61, v81
	v_rcp_f32_e32 v126, v108
	v_fma_f32 v139, -v100, v122, 1.0
	v_fmac_f32_e32 v121, v138, v121
	v_mul_f32_e32 v137, v97, v120
	v_fmac_f32_e32 v135, v151, v118
	v_fma_f32 v69, -v74, v134, v75
	v_fma_f32 v71, -v94, v136, v95
	v_fma_f32 v95, -v49, v144, v110
	v_div_fixup_f32 v49, v48, v53, v87
	v_div_fmas_f32 v48, v68, v116, v133
	s_mov_b64 vcc, s[26:27]
	ds_bpermute_b32 v67, v44, v66
	v_div_scale_f32 v101, s[16:17], v80, v60, v80
	v_fma_f32 v140, -v102, v123, 1.0
	v_fmac_f32_e32 v122, v139, v122
	v_mul_f32_e32 v138, v99, v121
	v_fma_f32 v153, -v96, v137, v97
	v_fma_f32 v70, -v92, v135, v93
	v_div_fixup_f32 v46, v46, v50, v88
	v_div_fmas_f32 v50, v69, v117, v134
	s_mov_b64 vcc, s[24:25]
	v_div_scale_f32 v103, s[14:15], v79, v63, v79
	v_fma_f32 v141, -v104, v124, 1.0
	v_fmac_f32_e32 v123, v140, v123
	v_mul_f32_e32 v139, v101, v122
	v_fma_f32 v154, -v98, v138, v99
	v_fmac_f32_e32 v137, v153, v120
	v_div_fixup_f32 v51, v50, v55, v85
	v_div_fmas_f32 v50, v70, v118, v135
	s_mov_b64 vcc, s[22:23]
	v_div_scale_f32 v105, s[12:13], v78, v62, v78
	v_fma_f32 v142, -v106, v125, 1.0
	v_fmac_f32_e32 v124, v141, v124
	v_mul_f32_e32 v140, v103, v123
	v_fma_f32 v155, -v100, v139, v101
	v_fmac_f32_e32 v138, v154, v121
	v_fma_f32 v72, -v96, v137, v97
	v_div_fixup_f32 v48, v48, v52, v86
	v_div_fmas_f32 v52, v71, v119, v136
	s_mov_b64 vcc, s[20:21]
	v_div_scale_f32 v107, s[10:11], v77, v65, v77
	v_fma_f32 v143, -v108, v126, 1.0
	v_fmac_f32_e32 v125, v142, v125
	v_mul_f32_e32 v141, v105, v124
	v_fma_f32 v156, -v102, v140, v103
	v_fmac_f32_e32 v139, v155, v122
	v_fma_f32 v73, -v98, v138, v99
	v_div_fixup_f32 v53, v52, v57, v83
	v_div_fmas_f32 v52, v72, v120, v137
	s_mov_b64 vcc, s[18:19]
	v_div_scale_f32 v109, s[6:7], v76, v64, v76
	v_fmac_f32_e32 v126, v143, v126
	v_mul_f32_e32 v142, v107, v125
	v_fma_f32 v157, -v104, v141, v105
	v_fmac_f32_e32 v140, v156, v123
	v_fma_f32 v74, -v100, v139, v101
	v_div_fixup_f32 v50, v50, v54, v84
	v_div_fmas_f32 v54, v73, v121, v138
	s_mov_b64 vcc, s[16:17]
	s_waitcnt lgkmcnt(0)
	v_add_f32_e32 v66, v66, v67
	v_mul_f32_e32 v143, v109, v126
	v_fma_f32 v158, -v106, v142, v107
	v_fmac_f32_e32 v141, v157, v124
	v_fma_f32 v75, -v102, v140, v103
	v_div_fixup_f32 v55, v54, v61, v81
	v_div_fmas_f32 v54, v74, v122, v139
	s_mov_b64 vcc, s[14:15]
	ds_bpermute_b32 v67, v45, v66
	v_fma_f32 v159, -v108, v143, v109
	v_fmac_f32_e32 v142, v158, v125
	v_fma_f32 v92, -v104, v141, v105
	v_div_fixup_f32 v52, v52, v56, v82
	v_div_fmas_f32 v56, v75, v123, v140
	s_mov_b64 vcc, s[12:13]
	v_fmac_f32_e32 v143, v159, v126
	v_fma_f32 v93, -v106, v142, v107
	v_div_fixup_f32 v57, v56, v63, v79
	v_div_fmas_f32 v56, v92, v124, v141
	s_mov_b64 vcc, s[10:11]
	v_fma_f32 v94, -v108, v143, v109
	v_div_fixup_f32 v54, v54, v60, v80
	v_div_fmas_f32 v60, v93, v125, v142
	s_mov_b64 vcc, s[6:7]
	v_div_fixup_f32 v61, v60, v65, v77
	v_div_fmas_f32 v60, v94, v126, v143
	s_mov_b64 vcc, s[8:9]
	v_fma_f32 v96, -v111, v145, v112
	v_div_fixup_f32 v56, v56, v62, v78
	v_div_fmas_f32 v62, v95, v127, v144
	s_waitcnt lgkmcnt(0)
	v_add_f32_e32 v63, v66, v67
	s_mov_b64 vcc, s[4:5]
	v_div_fixup_f32 v59, v62, v59, v91
	v_div_fmas_f32 v62, v96, v128, v145
	v_fmamk_f32 v63, v63, 0x3b800000, v27
	v_div_fixup_f32 v58, v62, v58, v90
	v_mul_f32_e32 v62, 0x4b800000, v63
	v_cmp_gt_f32_e32 vcc, s58, v63
	v_div_fixup_f32 v60, v60, v64, v76
	s_nop 0
	v_cndmask_b32_e32 v62, v63, v62, vcc
	v_rsq_f32_e32 v62, v62
	s_nop 0
	v_mul_f32_e32 v63, 0x45800000, v62
	v_cndmask_b32_e32 v62, v62, v63, vcc
	v_pk_mul_f32 v[40:41], v[40:41], v[62:63] op_sel_hi:[1,0]
	v_pk_mul_f32 v[38:39], v[38:39], v[62:63] op_sel_hi:[1,0]
	v_pk_mul_f32 v[36:37], v[36:37], v[62:63] op_sel_hi:[1,0]
	v_pk_mul_f32 v[34:35], v[34:35], v[62:63] op_sel_hi:[1,0]
	v_pk_mul_f32 v[24:25], v[24:25], v[62:63] op_sel_hi:[1,0]
	v_pk_mul_f32 v[22:23], v[22:23], v[62:63] op_sel_hi:[1,0]
	v_pk_mul_f32 v[20:21], v[20:21], v[62:63] op_sel_hi:[1,0]
	v_pk_mul_f32 v[18:19], v[18:19], v[62:63] op_sel_hi:[1,0]
	v_pk_mul_f32 v[14:15], v[14:15], v[40:41]
	v_pk_mul_f32 v[16:17], v[16:17], v[38:39]
	v_pk_mul_f32 v[10:11], v[10:11], v[36:37]
	v_pk_mul_f32 v[12:13], v[12:13], v[34:35]
	v_pk_mul_f32 v[6:7], v[6:7], v[24:25]
	v_pk_mul_f32 v[8:9], v[22:23], v[8:9]
	v_pk_mul_f32 v[2:3], v[20:21], v[2:3]
	v_pk_mul_f32 v[4:5], v[18:19], v[4:5]
	v_pk_mul_f32 v[14:15], v[60:61], v[14:15]
	v_pk_mul_f32 v[16:17], v[56:57], v[16:17]
	v_pk_mul_f32 v[10:11], v[54:55], v[10:11]
	v_pk_mul_f32 v[12:13], v[52:53], v[12:13]
	v_pk_mul_f32 v[6:7], v[50:51], v[6:7]
	v_pk_mul_f32 v[8:9], v[48:49], v[8:9]
	v_pk_mul_f32 v[18:19], v[46:47], v[2:3]
	v_pk_mul_f32 v[20:21], v[58:59], v[4:5]
	v_cvt_pk_bf16_f32 v2, v14, v15
	v_cvt_pk_bf16_f32 v3, v16, v17
	v_cvt_pk_bf16_f32 v4, v10, v11
	v_cvt_pk_bf16_f32 v5, v12, v13
	v_cvt_pk_bf16_f32 v6, v6, v7
	v_cvt_pk_bf16_f32 v7, v8, v9
	v_cvt_pk_bf16_f32 v8, v18, v19
	v_cvt_pk_bf16_f32 v9, v20, v21
	global_store_dwordx4 v[32:33], v[2:5], off offset:-28
	global_store_dwordx4 v[32:33], v[6:9], off offset:-12
	s_andn2_b64 exec, exec, s[52:53]
	s_cbranch_execnz .LBB0_492

.LBB0_1229:
	s_cmp_gt_i32 s44, 14
	s_cselect_b64 s[2:3], -1, 0
	s_cmp_lt_i32 s45, 15
	s_cselect_b64 s[4:5], -1, 0
	s_or_b64 s[2:3], s[2:3], s[4:5]
	s_and_b64 vcc, exec, s[2:3]
	s_cbranch_vccnz .LBB0_1287
	s_load_dword s33, s[0:1], 0xf0
	s_waitcnt vmcnt(1)
	v_lshl_or_b32 v26, s66, 2, v131
	s_add_u32 s2, s0, 0xf0
	s_movk_i32 s4, 0x3000
	v_and_b32_e32 v1, 0x3ff, v0
	s_addc_u32 s3, s1, 0
	v_cmp_gt_i32_e32 vcc, s4, v26
	s_and_saveexec_b64 s[36:37], vcc
	s_cbranch_execz .LBB0_1233
	v_mbcnt_lo_u32_b32 v2, -1, 0
	v_mbcnt_hi_u32_b32 v2, -1, v2
	v_and_b32_e32 v4, 64, v2
	v_xor_b32_e32 v3, 1, v2
	v_add_u32_e32 v4, 64, v4
	v_cmp_lt_i32_e32 vcc, v3, v4
	v_ashrrev_i32_e32 v27, 31, v26
	s_waitcnt lgkmcnt(0)
	s_lshl_b32 s46, s33, 2
	v_cndmask_b32_e32 v3, v2, v3, vcc
	v_lshlrev_b32_e32 v42, 2, v3
	v_xor_b32_e32 v3, 2, v2
	v_cmp_lt_i32_e32 vcc, v3, v4
	s_mov_b64 s[4:5], 0x18d2401c
	s_ashr_i32 s47, s46, 31
	v_cndmask_b32_e32 v3, v2, v3, vcc
	v_lshlrev_b32_e32 v43, 2, v3
	v_xor_b32_e32 v3, 4, v2
	v_cmp_lt_i32_e32 vcc, v3, v4
	s_mov_b32 s52, 0xfe7fffe4
	s_mov_b32 s54, 0xf85fffe4
	v_cndmask_b32_e32 v3, v2, v3, vcc
	v_lshlrev_b32_e32 v44, 2, v3
	v_xor_b32_e32 v3, 8, v2
	v_cmp_lt_i32_e32 vcc, v3, v4
	v_and_b32_e32 v4, 63, v1
	s_lshl_b64 s[48:49], s[46:47], 11
	v_cndmask_b32_e32 v2, v2, v3, vcc
	v_lshlrev_b32_e32 v45, 2, v2
	v_lshlrev_b32_e32 v2, 6, v1
	v_and_b32_e32 v2, 0x3c0, v2
	v_mov_b32_e32 v3, 0
	v_lshl_add_u64 v[28:29], s[92:93], 0, v[2:3]
	v_lshlrev_b64 v[2:3], 11, v[26:27]
	v_lshl_or_b32 v2, v4, 5, v2
	v_lshl_add_u64 v[2:3], s[42:43], 0, v[2:3]
	s_waitcnt vmcnt(0)
	v_lshl_add_u64 v[30:31], v[2:3], 0, s[4:5]
	s_mov_b64 s[50:51], 0
	s_mov_b32 s53, -1
	s_mov_b32 s55, -1
	s_mov_b32 s47, 0xf8600000
	v_mov_b32_e32 v27, 0x358637bd
	s_mov_b32 s56, 0x800000
	s_movk_i32 s57, 0x2fff
	global_load_dwordx4 v[224:227], v[28:29], off offset:1072
	global_load_dwordx4 v[228:231], v[28:29], off offset:1056
	global_load_dwordx4 v[232:235], v[28:29], off offset:1040
	global_load_dwordx4 v[236:239], v[28:29], off offset:1024
	s_waitcnt vmcnt(0)
.LBB0_1232:
	v_add_co_u32_e32 v32, vcc, 0xfe800000, v30
	global_load_dwordx4 v[18:21], v[30:31], off offset:-12
	global_load_dwordx4 v[22:25], v[30:31], off offset:-28
	v_addc_co_u32_e32 v33, vcc, -1, v31, vcc
	v_add_co_u32_e32 v58, vcc, s47, v30
	v_lshl_add_u64 v[36:37], v[30:31], 0, s[52:53]
	v_mov_b32_e32 v2, v224
	v_mov_b32_e32 v3, v225
	v_mov_b32_e32 v4, v226
	v_mov_b32_e32 v5, v227
	v_mov_b32_e32 v6, v228
	v_mov_b32_e32 v7, v229
	v_mov_b32_e32 v8, v230
	v_mov_b32_e32 v9, v231
	v_mov_b32_e32 v10, v232
	v_mov_b32_e32 v11, v233
	v_mov_b32_e32 v12, v234
	v_mov_b32_e32 v13, v235
	v_mov_b32_e32 v14, v236
	v_mov_b32_e32 v15, v237
	v_mov_b32_e32 v16, v238
	v_mov_b32_e32 v17, v239
	global_load_dwordx4 v[38:41], v[32:33], off offset:-28
	global_load_dwordx4 v[46:49], v[36:37], off offset:16
	v_addc_co_u32_e32 v59, vcc, -1, v31, vcc
	v_lshl_add_u64 v[34:35], v[30:31], 0, s[54:55]
	global_load_dwordx4 v[50:53], v[58:59], off offset:-28
	global_load_dwordx4 v[54:57], v[34:35], off offset:16
	v_add_u32_e32 v26, s46, v26
	v_cmp_lt_i32_e64 s[4:5], s57, v26
	s_or_b64 s[50:51], s[4:5], s[50:51]
	v_lshl_add_u64 v[30:31], v[30:31], 0, s[48:49]
	s_waitcnt vmcnt(5)
	v_lshlrev_b32_e32 v62, 16, v20
	s_waitcnt vmcnt(4)
	v_lshlrev_b32_e32 v58, 16, v22
	v_and_b32_e32 v59, 0xffff0000, v22
	v_lshlrev_b32_e32 v60, 16, v23
	v_and_b32_e32 v61, 0xffff0000, v23
	v_lshlrev_b32_e32 v36, 16, v24
	v_and_b32_e32 v37, 0xffff0000, v24
	v_lshlrev_b32_e32 v34, 16, v25
	v_and_b32_e32 v35, 0xffff0000, v25
	v_lshlrev_b32_e32 v24, 16, v18
	v_and_b32_e32 v25, 0xffff0000, v18
	v_lshlrev_b32_e32 v22, 16, v19
	v_and_b32_e32 v23, 0xffff0000, v19
	v_and_b32_e32 v63, 0xffff0000, v20
	v_lshlrev_b32_e32 v18, 16, v21
	v_and_b32_e32 v19, 0xffff0000, v21
	s_waitcnt vmcnt(3)
	v_lshlrev_b32_e32 v64, 16, v38
	v_and_b32_e32 v65, 0xffff0000, v38
	v_lshlrev_b32_e32 v38, 16, v39
	v_and_b32_e32 v39, 0xffff0000, v39
	v_lshlrev_b32_e32 v66, 16, v40
	v_and_b32_e32 v67, 0xffff0000, v40
	v_lshlrev_b32_e32 v40, 16, v41
	v_and_b32_e32 v41, 0xffff0000, v41
	s_waitcnt vmcnt(2)
	v_lshlrev_b32_e32 v68, 16, v46
	v_and_b32_e32 v69, 0xffff0000, v46
	v_lshlrev_b32_e32 v46, 16, v47
	v_and_b32_e32 v47, 0xffff0000, v47
	v_lshlrev_b32_e32 v20, 16, v48
	v_and_b32_e32 v21, 0xffff0000, v48
	v_lshlrev_b32_e32 v48, 16, v49
	v_and_b32_e32 v49, 0xffff0000, v49
	s_waitcnt vmcnt(0)
	v_lshlrev_b32_e32 v88, 16, v56
	v_and_b32_e32 v89, 0xffff0000, v56
	v_pk_add_f32 v[18:19], v[48:49], v[18:19]
	v_pk_add_f32 v[20:21], v[20:21], v[62:63]
	v_pk_add_f32 v[22:23], v[46:47], v[22:23]
	v_pk_add_f32 v[24:25], v[68:69], v[24:25]
	v_pk_add_f32 v[34:35], v[40:41], v[34:35]
	v_pk_add_f32 v[36:37], v[66:67], v[36:37]
	v_pk_add_f32 v[38:39], v[38:39], v[60:61]
	v_pk_add_f32 v[40:41], v[64:65], v[58:59]
	v_lshlrev_b32_e32 v80, 16, v52
	v_and_b32_e32 v81, 0xffff0000, v52
	v_lshlrev_b32_e32 v82, 16, v53
	v_and_b32_e32 v83, 0xffff0000, v53
	v_lshlrev_b32_e32 v84, 16, v54
	v_and_b32_e32 v85, 0xffff0000, v54
	v_lshlrev_b32_e32 v90, 16, v57
	v_and_b32_e32 v91, 0xffff0000, v57
	v_mov_b32_e32 v48, v21
	v_mov_b32_e32 v49, v19
	v_mul_f32_e32 v62, 0xbfb8aa3b, v88
	v_mul_f32_e32 v63, 0xbfb8aa3b, v89
	v_mov_b32_e32 v52, v25
	v_mov_b32_e32 v53, v23
	v_mov_b32_e32 v56, v37
	v_mov_b32_e32 v57, v35
	v_pk_mul_f32 v[58:59], v[38:39], v[38:39]
	v_pk_mul_f32 v[60:61], v[40:41], v[40:41]
	v_lshlrev_b32_e32 v76, 16, v50
	v_and_b32_e32 v77, 0xffff0000, v50
	v_lshlrev_b32_e32 v78, 16, v51
	v_and_b32_e32 v79, 0xffff0000, v51
	v_lshlrev_b32_e32 v86, 16, v55
	v_and_b32_e32 v87, 0xffff0000, v55
	v_mov_b32_e32 v46, v20
	v_mov_b32_e32 v47, v18
	v_mov_b32_e32 v50, v24
	v_mov_b32_e32 v51, v22
	v_mul_f32_e32 v66, 0xbfb8aa3b, v84
	v_mul_f32_e32 v67, 0xbfb8aa3b, v85
	v_mov_b32_e32 v54, v36
	v_mov_b32_e32 v55, v34
	v_pk_mul_f32 v[48:49], v[48:49], v[48:49]
	v_exp_f32_e32 v62, v62
	v_exp_f32_e32 v63, v63
	v_pk_mul_f32 v[52:53], v[52:53], v[52:53]
	v_pk_mul_f32 v[56:57], v[56:57], v[56:57]
	v_add_f32_e32 v94, v58, v59
	v_add_f32_e32 v60, v60, v61
	v_mul_f32_e32 v92, 0xbfb8aa3b, v90
	v_mul_f32_e32 v93, 0xbfb8aa3b, v91
	v_exp_f32_e32 v66, v66
	v_exp_f32_e32 v67, v67
	v_pk_fma_f32 v[46:47], v[46:47], v[46:47], v[48:49]
	v_pk_fma_f32 v[48:49], v[50:51], v[50:51], v[52:53]
	v_pk_fma_f32 v[50:51], v[54:55], v[54:55], v[56:57]
	v_add_f32_e32 v52, v60, v94
	v_mul_f32_e32 v64, 0xbfb8aa3b, v86
	v_mul_f32_e32 v65, 0xbfb8aa3b, v87
	v_mul_f32_e32 v68, 0xbfb8aa3b, v82
	v_mul_f32_e32 v69, 0xbfb8aa3b, v83
	v_exp_f32_e32 v58, v92
	v_exp_f32_e32 v59, v93
	v_add_f32_e32 v50, v52, v50
	v_mul_f32_e32 v70, 0xbfb8aa3b, v80
	v_mul_f32_e32 v71, 0xbfb8aa3b, v81
	v_exp_f32_e32 v64, v64
	v_exp_f32_e32 v65, v65
	v_exp_f32_e32 v68, v68
	v_exp_f32_e32 v69, v69
	v_add_f32_e32 v92, v50, v51
	v_mul_f32_e32 v72, 0xbfb8aa3b, v78
	v_mul_f32_e32 v73, 0xbfb8aa3b, v79
	v_exp_f32_e32 v70, v70
	v_exp_f32_e32 v71, v71
	v_pk_add_f32 v[50:51], v[62:63], 1.0 op_sel_hi:[1,0]
	v_add_f32_e32 v48, v92, v48
	v_mul_f32_e32 v74, 0xbfb8aa3b, v76
	v_mul_f32_e32 v75, 0xbfb8aa3b, v77
	v_exp_f32_e32 v72, v72
	v_exp_f32_e32 v73, v73
	v_pk_add_f32 v[54:55], v[66:67], 1.0 op_sel_hi:[1,0]
	v_div_scale_f32 v66, s[4:5], v51, v51, v89
	v_add_f32_e32 v48, v48, v49
	v_exp_f32_e32 v74, v74
	v_exp_f32_e32 v75, v75
	v_pk_add_f32 v[58:59], v[58:59], 1.0 op_sel_hi:[1,0]
	v_rcp_f32_e32 v113, v66
	v_add_f32_e32 v46, v48, v46
	v_pk_add_f32 v[52:53], v[64:65], 1.0 op_sel_hi:[1,0]
	v_pk_add_f32 v[56:57], v[68:69], 1.0 op_sel_hi:[1,0]
	v_div_scale_f32 v68, s[4:5], v50, v50, v88
	v_div_scale_f32 v49, s[4:5], v59, v59, v91
	v_add_f32_e32 v46, v46, v47
	v_pk_add_f32 v[60:61], v[70:71], 1.0 op_sel_hi:[1,0]
	v_div_scale_f32 v70, s[4:5], v53, v53, v87
	v_rcp_f32_e32 v114, v68
	v_rcp_f32_e32 v127, v49
	ds_bpermute_b32 v47, v42, v46
	v_pk_add_f32 v[62:63], v[72:73], 1.0 op_sel_hi:[1,0]
	v_div_scale_f32 v72, s[4:5], v52, v52, v86
	v_div_scale_f32 v111, s[4:5], v58, v58, v90
	v_rcp_f32_e32 v115, v70
	v_pk_add_f32 v[64:65], v[74:75], 1.0 op_sel_hi:[1,0]
	v_div_scale_f32 v74, s[4:5], v55, v55, v85
	v_div_scale_f32 v94, s[4:5], v57, v57, v83
	v_rcp_f32_e32 v116, v72
	v_rcp_f32_e32 v128, v111
	v_fma_f32 v48, -v66, v113, 1.0
	v_div_scale_f32 v67, vcc, v89, v51, v89
	v_div_scale_f32 v92, s[4:5], v54, v54, v84
	v_rcp_f32_e32 v117, v74
	v_rcp_f32_e32 v119, v94
	v_fmac_f32_e32 v113, v48, v113
	v_rcp_f32_e32 v118, v92
	v_fma_f32 v129, -v68, v114, 1.0
	v_fma_f32 v144, -v49, v127, 1.0
	v_mul_f32_e32 v48, v67, v113
	v_div_scale_f32 v69, s[34:35], v88, v50, v88
	v_div_scale_f32 v96, s[4:5], v56, v56, v82
	v_div_scale_f32 v110, s[8:9], v91, v59, v91
	v_fma_f32 v132, -v70, v115, 1.0
	v_fmac_f32_e32 v114, v129, v114
	v_fmac_f32_e32 v127, v144, v127
	v_fma_f32 v146, -v66, v48, v67
	s_waitcnt lgkmcnt(0)
	v_add_f32_e32 v160, v46, v47
	v_div_scale_f32 v71, s[30:31], v87, v53, v87
	v_div_scale_f32 v98, s[4:5], v61, v61, v81
	v_div_scale_f32 v100, s[4:5], v60, v60, v80
	v_div_scale_f32 v102, s[4:5], v63, v63, v79
	v_div_scale_f32 v104, s[4:5], v62, v62, v78
	v_div_scale_f32 v106, s[4:5], v65, v65, v77
	v_div_scale_f32 v108, s[4:5], v64, v64, v76
	v_rcp_f32_e32 v120, v96
	v_fma_f32 v133, -v72, v116, 1.0
	v_fma_f32 v145, -v111, v128, 1.0
	v_fmac_f32_e32 v115, v132, v115
	v_mul_f32_e32 v129, v69, v114
	v_mul_f32_e32 v144, v110, v127
	v_fmac_f32_e32 v48, v146, v113
	ds_bpermute_b32 v146, v43, v160
	v_div_scale_f32 v73, s[28:29], v86, v52, v86
	v_div_scale_f32 v112, s[4:5], v90, v58, v90
	v_rcp_f32_e32 v121, v98
	v_fma_f32 v134, -v74, v117, 1.0
	v_fma_f32 v136, -v94, v119, 1.0
	v_fmac_f32_e32 v116, v133, v116
	v_fmac_f32_e32 v128, v145, v128
	v_mul_f32_e32 v132, v71, v115
	v_fma_f32 v147, -v68, v129, v69
	v_fma_f32 v46, -v49, v144, v110
	v_div_scale_f32 v75, s[26:27], v85, v55, v85
	v_div_scale_f32 v95, s[22:23], v83, v57, v83
	v_rcp_f32_e32 v122, v100
	v_fma_f32 v135, -v92, v118, 1.0
	v_fmac_f32_e32 v117, v134, v117
	v_fmac_f32_e32 v119, v136, v119
	v_mul_f32_e32 v133, v73, v116
	v_mul_f32_e32 v145, v112, v128
	v_fma_f32 v148, -v70, v132, v71
	v_fmac_f32_e32 v129, v147, v114
	v_fmac_f32_e32 v144, v46, v127
	v_fma_f32 v46, -v66, v48, v67
	v_div_scale_f32 v93, s[24:25], v84, v54, v84
	v_rcp_f32_e32 v123, v102
	v_fmac_f32_e32 v118, v135, v118
	v_mul_f32_e32 v134, v75, v117
	v_mul_f32_e32 v136, v95, v119
	v_fma_f32 v149, -v72, v133, v73
	v_fma_f32 v47, -v111, v145, v112
	v_fmac_f32_e32 v132, v148, v115
	v_fma_f32 v66, -v68, v129, v69
	v_div_fmas_f32 v46, v46, v113, v48
	s_mov_b64 vcc, s[34:35]
	v_rcp_f32_e32 v124, v104
	v_fma_f32 v137, -v96, v120, 1.0
	v_mul_f32_e32 v135, v93, v118
	v_fma_f32 v150, -v74, v134, v75
	v_fma_f32 v152, -v94, v136, v95
	v_fmac_f32_e32 v133, v149, v116
	v_fmac_f32_e32 v145, v47, v128
	v_fma_f32 v67, -v70, v132, v71
	v_div_fixup_f32 v47, v46, v51, v89
	v_div_fmas_f32 v46, v66, v114, v129
	s_mov_b64 vcc, s[30:31]
	v_div_scale_f32 v97, s[20:21], v82, v56, v82
	v_rcp_f32_e32 v125, v106
	v_fma_f32 v138, -v98, v121, 1.0
	v_fmac_f32_e32 v120, v137, v120
	v_fma_f32 v151, -v92, v135, v93
	v_fmac_f32_e32 v134, v150, v117
	v_fmac_f32_e32 v136, v152, v119
	v_fma_f32 v68, -v72, v133, v73
	v_div_fmas_f32 v48, v67, v115, v132
	s_mov_b64 vcc, s[28:29]
	s_waitcnt lgkmcnt(0)
	v_add_f32_e32 v66, v160, v146
	v_div_scale_f32 v99, s[18:19], v81, v61, v81
	v_rcp_f32_e32 v126, v108
	v_fma_f32 v139, -v100, v122, 1.0
	v_fmac_f32_e32 v121, v138, v121
	v_mul_f32_e32 v137, v97, v120
	v_fmac_f32_e32 v135, v151, v118
	v_fma_f32 v69, -v74, v134, v75
	v_fma_f32 v71, -v94, v136, v95
	v_fma_f32 v95, -v49, v144, v110
	v_div_fixup_f32 v49, v48, v53, v87
	v_div_fmas_f32 v48, v68, v116, v133
	s_mov_b64 vcc, s[26:27]
	ds_bpermute_b32 v67, v44, v66
	v_div_scale_f32 v101, s[16:17], v80, v60, v80
	v_fma_f32 v140, -v102, v123, 1.0
	v_fmac_f32_e32 v122, v139, v122
	v_mul_f32_e32 v138, v99, v121
	v_fma_f32 v153, -v96, v137, v97
	v_fma_f32 v70, -v92, v135, v93
	v_div_fixup_f32 v46, v46, v50, v88
	v_div_fmas_f32 v50, v69, v117, v134
	s_mov_b64 vcc, s[24:25]
	v_div_scale_f32 v103, s[14:15], v79, v63, v79
	v_fma_f32 v141, -v104, v124, 1.0
	v_fmac_f32_e32 v123, v140, v123
	v_mul_f32_e32 v139, v101, v122
	v_fma_f32 v154, -v98, v138, v99
	v_fmac_f32_e32 v137, v153, v120
	v_div_fixup_f32 v51, v50, v55, v85
	v_div_fmas_f32 v50, v70, v118, v135
	s_mov_b64 vcc, s[22:23]
	v_div_scale_f32 v105, s[12:13], v78, v62, v78
	v_fma_f32 v142, -v106, v125, 1.0
	v_fmac_f32_e32 v124, v141, v124
	v_mul_f32_e32 v140, v103, v123
	v_fma_f32 v155, -v100, v139, v101
	v_fmac_f32_e32 v138, v154, v121
	v_fma_f32 v72, -v96, v137, v97
	v_div_fixup_f32 v48, v48, v52, v86
	v_div_fmas_f32 v52, v71, v119, v136
	s_mov_b64 vcc, s[20:21]
	v_div_scale_f32 v107, s[10:11], v77, v65, v77
	v_fma_f32 v143, -v108, v126, 1.0
	v_fmac_f32_e32 v125, v142, v125
	v_mul_f32_e32 v141, v105, v124
	v_fma_f32 v156, -v102, v140, v103
	v_fmac_f32_e32 v139, v155, v122
	v_fma_f32 v73, -v98, v138, v99
	v_div_fixup_f32 v53, v52, v57, v83
	v_div_fmas_f32 v52, v72, v120, v137
	s_mov_b64 vcc, s[18:19]
	v_div_scale_f32 v109, s[6:7], v76, v64, v76
	v_fmac_f32_e32 v126, v143, v126
	v_mul_f32_e32 v142, v107, v125
	v_fma_f32 v157, -v104, v141, v105
	v_fmac_f32_e32 v140, v156, v123
	v_fma_f32 v74, -v100, v139, v101
	v_div_fixup_f32 v50, v50, v54, v84
	v_div_fmas_f32 v54, v73, v121, v138
	s_mov_b64 vcc, s[16:17]
	s_waitcnt lgkmcnt(0)
	v_add_f32_e32 v66, v66, v67
	v_mul_f32_e32 v143, v109, v126
	v_fma_f32 v158, -v106, v142, v107
	v_fmac_f32_e32 v141, v157, v124
	v_fma_f32 v75, -v102, v140, v103
	v_div_fixup_f32 v55, v54, v61, v81
	v_div_fmas_f32 v54, v74, v122, v139
	s_mov_b64 vcc, s[14:15]
	ds_bpermute_b32 v67, v45, v66
	v_fma_f32 v159, -v108, v143, v109
	v_fmac_f32_e32 v142, v158, v125
	v_fma_f32 v92, -v104, v141, v105
	v_div_fixup_f32 v52, v52, v56, v82
	v_div_fmas_f32 v56, v75, v123, v140
	s_mov_b64 vcc, s[12:13]
	v_fmac_f32_e32 v143, v159, v126
	v_fma_f32 v93, -v106, v142, v107
	v_div_fixup_f32 v57, v56, v63, v79
	v_div_fmas_f32 v56, v92, v124, v141
	s_mov_b64 vcc, s[10:11]
	v_fma_f32 v94, -v108, v143, v109
	v_div_fixup_f32 v54, v54, v60, v80
	v_div_fmas_f32 v60, v93, v125, v142
	s_mov_b64 vcc, s[6:7]
	v_div_fixup_f32 v61, v60, v65, v77
	v_div_fmas_f32 v60, v94, v126, v143
	s_mov_b64 vcc, s[8:9]
	v_fma_f32 v96, -v111, v145, v112
	v_div_fixup_f32 v56, v56, v62, v78
	v_div_fmas_f32 v62, v95, v127, v144
	s_waitcnt lgkmcnt(0)
	v_add_f32_e32 v63, v66, v67
	s_mov_b64 vcc, s[4:5]
	v_div_fixup_f32 v59, v62, v59, v91
	v_div_fmas_f32 v62, v96, v128, v145
	v_fmamk_f32 v63, v63, 0x3b800000, v27
	v_div_fixup_f32 v58, v62, v58, v90
	v_mul_f32_e32 v62, 0x4b800000, v63
	v_cmp_gt_f32_e32 vcc, s56, v63
	v_div_fixup_f32 v60, v60, v64, v76
	s_nop 0
	v_cndmask_b32_e32 v62, v63, v62, vcc
	v_rsq_f32_e32 v62, v62
	s_nop 0
	v_mul_f32_e32 v63, 0x45800000, v62
	v_cndmask_b32_e32 v62, v62, v63, vcc
	v_pk_mul_f32 v[40:41], v[40:41], v[62:63] op_sel_hi:[1,0]
	v_pk_mul_f32 v[38:39], v[38:39], v[62:63] op_sel_hi:[1,0]
	v_pk_mul_f32 v[36:37], v[36:37], v[62:63] op_sel_hi:[1,0]
	v_pk_mul_f32 v[34:35], v[34:35], v[62:63] op_sel_hi:[1,0]
	v_pk_mul_f32 v[24:25], v[24:25], v[62:63] op_sel_hi:[1,0]
	v_pk_mul_f32 v[22:23], v[22:23], v[62:63] op_sel_hi:[1,0]
	v_pk_mul_f32 v[20:21], v[20:21], v[62:63] op_sel_hi:[1,0]
	v_pk_mul_f32 v[18:19], v[18:19], v[62:63] op_sel_hi:[1,0]
	v_pk_mul_f32 v[14:15], v[14:15], v[40:41]
	v_pk_mul_f32 v[16:17], v[16:17], v[38:39]
	v_pk_mul_f32 v[10:11], v[10:11], v[36:37]
	v_pk_mul_f32 v[12:13], v[12:13], v[34:35]
	v_pk_mul_f32 v[6:7], v[6:7], v[24:25]
	v_pk_mul_f32 v[8:9], v[22:23], v[8:9]
	v_pk_mul_f32 v[2:3], v[20:21], v[2:3]
	v_pk_mul_f32 v[4:5], v[18:19], v[4:5]
	v_pk_mul_f32 v[14:15], v[60:61], v[14:15]
	v_pk_mul_f32 v[16:17], v[56:57], v[16:17]
	v_pk_mul_f32 v[10:11], v[54:55], v[10:11]
	v_pk_mul_f32 v[12:13], v[52:53], v[12:13]
	v_pk_mul_f32 v[6:7], v[50:51], v[6:7]
	v_pk_mul_f32 v[8:9], v[48:49], v[8:9]
	v_pk_mul_f32 v[18:19], v[46:47], v[2:3]
	v_pk_mul_f32 v[20:21], v[58:59], v[4:5]
	v_cvt_pk_bf16_f32 v2, v14, v15
	v_cvt_pk_bf16_f32 v3, v16, v17
	v_cvt_pk_bf16_f32 v4, v10, v11
	v_cvt_pk_bf16_f32 v5, v12, v13
	v_cvt_pk_bf16_f32 v6, v6, v7
	v_cvt_pk_bf16_f32 v7, v8, v9
	v_cvt_pk_bf16_f32 v8, v18, v19
	v_cvt_pk_bf16_f32 v9, v20, v21
	global_store_dwordx4 v[32:33], v[2:5], off offset:-28
	global_store_dwordx4 v[32:33], v[6:9], off offset:-12
	s_andn2_b64 exec, exec, s[50:51]
	s_cbranch_execnz .LBB0_1232
